# MLA: waves 4-7 staggered by half a tile (two barriers per tile, group B writes its tile parts at end of QK half and prefetches half an iteration earlier) to pair pipe-bound QK half with issue-bound so
# baseline (speedup 1.0000x reference)
.LBB0_1370:
	v_exp_f32_e32 v96, v96
	v_exp_f32_e32 v97, v97
	v_exp_f32_e32 v98, v98
	v_exp_f32_e32 v99, v99
	v_exp_f32_e32 v100, v100
	v_exp_f32_e32 v101, v101
	v_exp_f32_e32 v102, v102
	v_exp_f32_e32 v103, v103
	v_cvt_pk_bf16_f32 v96, v96, v97
	v_cvt_pk_bf16_f32 v97, v98, v99
	v_cvt_pk_bf16_f32 v98, v100, v101
	v_cvt_pk_bf16_f32 v99, v102, v103
	v_exp_f32_e32 v88, v88
	v_exp_f32_e32 v89, v89
	v_exp_f32_e32 v90, v90
	v_exp_f32_e32 v91, v91
	v_exp_f32_e32 v100, v92
	v_exp_f32_e32 v101, v93
	v_exp_f32_e32 v102, v94
	v_exp_f32_e32 v103, v95
	v_mov_b64_e32 v[136:137], s[14:15]
	v_mov_b64_e32 v[134:135], s[12:13]
	v_mov_b32_e32 v109, v108
	v_mov_b32_e32 v110, v108
	v_mov_b32_e32 v111, v108
	s_waitcnt lgkmcnt(1)
	v_mov_b32_e32 v105, v104
	v_mov_b32_e32 v106, v104
	s_waitcnt lgkmcnt(0)
	v_mov_b32_e32 v107, v104
	v_cvt_pk_bf16_f32 v88, v88, v89
	v_cvt_pk_bf16_f32 v89, v90, v91
	v_cvt_pk_bf16_f32 v90, v100, v101
	v_cvt_pk_bf16_f32 v91, v102, v103
	v_mfma_f32_16x16x32_bf16 v[100:103], v[68:71], v[96:99], v[108:111]
	v_exp_f32_e32 v113, v76
	v_exp_f32_e32 v115, v81
	v_exp_f32_e32 v117, v82
	v_mfma_f32_16x16x32_bf16 v[122:125], v[68:71], v[88:91], v[104:107]
	v_exp_f32_e32 v68, v77
	v_exp_f32_e32 v69, v78
	v_exp_f32_e32 v70, v79
	v_mfma_f32_16x16x32_bf16 v[76:79], v[64:67], v[96:99], v[108:111]
	v_exp_f32_e32 v71, v80
	v_cvt_pk_bf16_f32 v80, v113, v68
	v_cvt_pk_bf16_f32 v81, v69, v70
	v_mfma_f32_16x16x32_bf16 v[126:129], v[64:67], v[88:91], v[104:107]
	v_exp_f32_e32 v64, v83
	v_cvt_pk_bf16_f32 v82, v71, v115
	s_waitcnt vmcnt(1)
	ds_write_b128 v121, v[32:35] offset:13312
	v_mfma_f32_16x16x32_bf16 v[130:133], v[52:55], v[96:99], v[108:111]
	v_cvt_pk_bf16_f32 v83, v117, v64
	v_lshlrev_b32_e32 v144, 1, v116
	v_mfma_f32_16x16x32_bf16 v[138:141], v[52:55], v[88:91], v[104:107]
	v_exp_f32_e32 v52, v56
	v_exp_f32_e32 v53, v57
	v_exp_f32_e32 v54, v58
	v_exp_f32_e32 v55, v59
	v_exp_f32_e32 v56, v60
	v_exp_f32_e32 v57, v61
	v_exp_f32_e32 v58, v62
	v_exp_f32_e32 v59, v63
	v_mfma_f32_16x16x32_bf16 v[92:95], v[84:87], v[96:99], v[108:111]
	v_mfma_f32_16x16x32_bf16 v[84:87], v[84:87], v[88:91], v[104:107]
	v_mfma_f32_16x16x32_bf16 v[96:99], v[134:137], v[96:99], v[108:111]
	v_mfma_f32_16x16x32_bf16 v[88:91], v[134:137], v[88:91], v[104:107]
	s_nop 2
	v_cvt_pk_bf16_f32 v104, v52, v53
	v_cvt_pk_bf16_f32 v105, v54, v55
	v_cvt_pk_bf16_f32 v106, v56, v57
	v_cvt_pk_bf16_f32 v107, v58, v59
	v_mfma_f32_16x16x32_bf16 v[68:71], v[48:51], v[80:83], v[92:95]
	s_nop 0
	v_mfma_f32_16x16x32_bf16 v[64:67], v[48:51], v[104:107], v[84:87]
	v_mfma_f32_16x16x32_bf16 v[60:63], v[44:47], v[80:83], v[100:103]
	v_mfma_f32_16x16x32_bf16 v[56:59], v[44:47], v[104:107], v[122:125]
	v_mfma_f32_16x16x32_bf16 v[52:55], v[40:43], v[80:83], v[76:79]
	v_mfma_f32_16x16x32_bf16 v[48:51], v[40:43], v[104:107], v[126:129]
	v_mfma_f32_16x16x32_bf16 v[44:47], v[36:39], v[80:83], v[130:133]
	v_mfma_f32_16x16x32_bf16 v[40:43], v[36:39], v[104:107], v[138:141]
	v_mfma_f32_16x16x32_bf16 v[36:39], v[134:137], v[80:83], v[96:99]
	v_mfma_f32_16x16x32_bf16 v[32:35], v[134:137], v[104:107], v[88:91]
	s_and_saveexec_b64 s[26:27], s[6:7]
	v_lshl_add_u32 v76, v171, 1, v144
	ds_write_b128 v76, v[28:31] offset:13312
	s_or_b64 exec, exec, s[26:27]
	s_lshl_b32 s26, s43, 8
	v_mov_b32_e32 v115, v145
	s_addk_i32 s26, 0x7800
	s_mov_b32 s27, 1
	v_lshl_add_u64 v[160:161], s[0:1], 0, v[114:115]
	v_add_u32_e32 v177, 0x80, v119
	v_add_u32_e32 v178, 0x80, v120
	v_add_u32_e32 v179, 0x80, v118
	v_lshlrev_b32_e32 v180, 1, v112
	v_mov_b32_e32 v203, 0
	v_mov_b32_e32 v210, v179
	v_mov_b32_e32 v211, 0
	v_mov_b32_e32 v214, 0x800
	v_lshlrev_b64 v[212:213], 11, v[210:211]
	v_lshlrev_b64 v[210:211], 6, v[210:211]
	v_lshl_add_u64 v[210:211], v[152:153], 0, v[210:211]
	v_lshl_add_u64 v[212:213], v[150:151], 0, v[212:213]
	v_lshl_add_u64 v[210:211], v[210:211], 0, s[24:25]
	v_cndmask_b32_e64 v205, v211, v213, s[4:5]
	v_cndmask_b32_e64 v204, v210, v212, s[4:5]
	v_mov_b32_e32 v206, 64
	v_cndmask_b32_e64 v206, v206, v214, s[4:5]
	v_mov_b32_e32 v210, v177
	v_mov_b32_e32 v211, 0
	v_lshlrev_b64 v[212:213], 11, v[210:211]
	v_lshlrev_b64 v[210:211], 6, v[210:211]
	v_lshl_add_u64 v[212:213], v[156:157], 0, v[212:213]
	v_lshl_add_u64 v[210:211], v[154:155], 0, v[210:211]
	v_cndmask_b32_e64 v209, v211, v213, s[8:9]
	v_cndmask_b32_e64 v208, v210, v212, s[8:9]
	v_mov_b32_e32 v207, 64
	v_cndmask_b32_e64 v207, v207, v214, s[8:9]
	v_mov_b32_e32 v210, v178
	v_mov_b32_e32 v211, 0
	v_lshlrev_b64 v[210:211], 11, v[210:211]
	v_lshl_add_u64 v[216:217], v[160:161], 0, v[210:211]
	v_xor_b32_e32 v218, 0x80000000, v159
	v_xor_b32_e32 v222, 0x80000000, v158
	v_mov_b32_e32 v219, v218
	v_mov_b32_e32 v220, v218
	v_mov_b32_e32 v221, v218
	v_mov_b32_e32 v223, v222
	v_mov_b32_e32 v224, v222
	v_mov_b32_e32 v225, v222
	v_mov_b64_e32 v[228:229], s[12:13]
	v_mov_b64_e32 v[230:231], s[14:15]
	s_waitcnt vmcnt(0)
	ds_write_b128 v174, v[72:75] offset:36864
	s_waitcnt lgkmcnt(0)
	s_barrier
	v_readfirstlane_b32 s99, v162
	s_cmp_ge_u32 s99, 0x100
	s_cbranch_scc1 .LmB_entry
	s_branch .LBB0_1374

.LBB0_1378:
	s_barrier
	v_exp_f32_e32 v136, v136
	v_exp_f32_e32 v137, v137
	v_exp_f32_e32 v138, v138
	v_exp_f32_e32 v139, v139
	v_exp_f32_e32 v140, v140
	v_exp_f32_e32 v141, v141
	v_exp_f32_e32 v142, v142
	v_exp_f32_e32 v143, v143
	v_exp_f32_e32 v128, v128
	v_exp_f32_e32 v129, v129
	v_exp_f32_e32 v130, v130
	v_exp_f32_e32 v131, v131
	v_exp_f32_e32 v132, v132
	v_exp_f32_e32 v133, v133
	v_exp_f32_e32 v134, v134
	v_exp_f32_e32 v135, v135
	v_cvt_pk_bf16_f32 v136, v136, v137
	v_cvt_pk_bf16_f32 v137, v138, v139
	v_cvt_pk_bf16_f32 v138, v140, v141
	v_cvt_pk_bf16_f32 v139, v142, v143
	v_cvt_pk_bf16_f32 v128, v128, v129
	v_cvt_pk_bf16_f32 v129, v130, v131
	v_cvt_pk_bf16_f32 v130, v132, v133
	v_cvt_pk_bf16_f32 v131, v134, v135
	s_waitcnt lgkmcnt(0)
	v_mfma_f32_16x16x32_bf16 v[60:63], v[112:115], v[136:139], v[60:63]
	v_exp_f32_e32 v116, v116
	s_xor_b32 s43, s0, 1
	s_mul_i32 s46, s43, 0x3400
	v_mfma_f32_16x16x32_bf16 v[56:59], v[112:115], v[128:131], v[56:59]
	v_exp_f32_e32 v112, v117
	v_exp_f32_e32 v113, v118
	v_exp_f32_e32 v114, v119
	v_exp_f32_e32 v115, v120
	v_exp_f32_e32 v117, v121
	v_mfma_f32_16x16x32_bf16 v[52:55], v[108:111], v[136:139], v[52:55]
	v_exp_f32_e32 v118, v122
	v_mfma_f32_16x16x32_bf16 v[48:51], v[108:111], v[128:131], v[48:51]
	v_cvt_pk_bf16_f32 v108, v116, v112
	v_cvt_pk_bf16_f32 v109, v113, v114
	v_cvt_pk_bf16_f32 v110, v115, v117
	v_exp_f32_e32 v111, v123
	v_mfma_f32_16x16x32_bf16 v[44:47], v[96:99], v[136:139], v[44:47]
	v_cvt_pk_bf16_f32 v111, v118, v111
	v_mfma_f32_16x16x32_bf16 v[40:43], v[96:99], v[128:131], v[40:43]
	v_exp_f32_e32 v96, v100
	v_exp_f32_e32 v97, v101
	v_exp_f32_e32 v98, v102
	v_exp_f32_e32 v99, v103
	v_exp_f32_e32 v100, v104
	v_exp_f32_e32 v101, v105
	v_exp_f32_e32 v102, v106
	v_exp_f32_e32 v103, v107
	v_mfma_f32_16x16x32_bf16 v[68:71], v[124:127], v[136:139], v[68:71]
	v_cvt_pk_bf16_f32 v96, v96, v97
	v_cvt_pk_bf16_f32 v97, v98, v99
	v_cvt_pk_bf16_f32 v98, v100, v101
	v_mfma_f32_16x16x32_bf16 v[64:67], v[124:127], v[128:131], v[64:67]
	v_cvt_pk_bf16_f32 v99, v102, v103
	v_mfma_f32_16x16x32_bf16 v[36:39], v[228:231], v[136:139], v[36:39]
	v_mfma_f32_16x16x32_bf16 v[32:35], v[228:231], v[128:131], v[32:35]
	v_mfma_f32_16x16x32_bf16 v[68:71], v[92:95], v[108:111], v[68:71]
	v_mfma_f32_16x16x32_bf16 v[64:67], v[92:95], v[96:99], v[64:67]
	v_mfma_f32_16x16x32_bf16 v[60:63], v[88:91], v[108:111], v[60:63]
	v_mfma_f32_16x16x32_bf16 v[56:59], v[88:91], v[96:99], v[56:59]
	v_mfma_f32_16x16x32_bf16 v[52:55], v[84:87], v[108:111], v[52:55]
	v_mfma_f32_16x16x32_bf16 v[48:51], v[84:87], v[96:99], v[48:51]
	v_mfma_f32_16x16x32_bf16 v[44:47], v[80:83], v[108:111], v[44:47]
	v_mfma_f32_16x16x32_bf16 v[40:43], v[80:83], v[96:99], v[40:43]
	v_lshlrev_b32_e32 v80, 1, v170
	v_add3_u32 v80, s46, v80, v180
	s_waitcnt vmcnt(1)
	ds_write_b128 v80, v[72:75]
	v_mfma_f32_16x16x32_bf16 v[36:39], v[228:231], v[108:111], v[36:39]
	v_mfma_f32_16x16x32_bf16 v[32:35], v[228:231], v[96:99], v[32:35]
	s_and_saveexec_b64 s[0:1], s[6:7]
	s_cbranch_execz .LBB0_1373
	v_lshlrev_b32_e32 v72, 1, v171
	v_add3_u32 v72, s46, v72, v144
	ds_write_b128 v72, v[28:31]
	s_branch .LBB0_1373
.LmB_entry:
	s_mov_b32 s98, s42
	s_lshl_b32 s100, s98, 11
	s_mov_b32 s101, 0
	v_mul_u32_u24_e32 v202, s98, v206
	v_lshl_add_u64 v[232:233], v[204:205], 0, v[202:203]
	global_load_dwordx4 v[232:235], v[232:233], off
	v_lshl_add_u64 v[236:237], v[216:217], 0, s[100:101]
	global_load_dwordx4 v[236:239], v[236:237], off offset:128
	s_barrier
	s_branch .LmB_1374
.LmB_1373:
	s_add_i32 s27, s27, 1
	s_cmp_lg_u32 s27, 35
	s_waitcnt lgkmcnt(0)
	s_barrier
	s_cbranch_scc0 .LBB0_1380
.LmB_1374:
.LmB_1376:
	s_and_b32 s0, s27, 1
	s_mul_i32 s1, s0, 0x3400
	v_add_u32_e32 v124, s1, v175
	ds_read_b128 v[76:79], v124
	ds_read_b128 v[88:91], v124 offset:64
	s_waitcnt lgkmcnt(1)
	v_mfma_f32_16x16x32_bf16 v[92:95], v[76:79], v[20:23], v[218:221]
	ds_read_b128 v[96:99], v124 offset:3328
	ds_read_b128 v[100:103], v124 offset:128
	ds_read_b128 v[108:111], v124 offset:6656
	ds_read_b128 v[112:115], v124 offset:6720
	ds_read_b128 v[120:123], v124 offset:9984
	ds_read_b128 v[182:185], v124 offset:6784
	v_mfma_f32_16x16x32_bf16 v[76:79], v[76:79], v[24:27], v[222:225]
	s_mul_i32 s1, s0, 0x2800
	s_waitcnt lgkmcnt(5)
	v_mfma_f32_16x16x32_bf16 v[104:107], v[96:99], v[20:23], v[218:221]
	v_mfma_f32_16x16x32_bf16 v[96:99], v[96:99], v[24:27], v[222:225]
	s_waitcnt lgkmcnt(3)
	v_mfma_f32_16x16x32_bf16 v[116:119], v[108:111], v[20:23], v[218:221]
	v_mfma_f32_16x16x32_bf16 v[108:111], v[108:111], v[24:27], v[222:225]
	s_waitcnt lgkmcnt(1)
	v_mfma_f32_16x16x32_bf16 v[80:83], v[120:123], v[20:23], v[218:221]
	v_mfma_f32_16x16x32_bf16 v[84:87], v[120:123], v[24:27], v[222:225]
	v_mfma_f32_16x16x32_bf16 v[92:95], v[88:91], v[12:15], v[92:95]
	v_mfma_f32_16x16x32_bf16 v[76:79], v[88:91], v[16:19], v[76:79]
	ds_read_b128 v[88:91], v124 offset:3392
	ds_read_b128 v[120:123], v124 offset:3456
	s_waitcnt lgkmcnt(1)
	v_mfma_f32_16x16x32_bf16 v[104:107], v[88:91], v[12:15], v[104:107]
	v_mfma_f32_16x16x32_bf16 v[88:91], v[88:91], v[16:19], v[96:99]
	s_nop 2
	ds_read_b128 v[96:99], v124 offset:10048
	ds_read_b128 v[190:193], v124 offset:10112
	s_waitcnt lgkmcnt(1)
	v_mfma_f32_16x16x32_bf16 v[194:197], v[96:99], v[12:15], v[80:83]
	s_nop 2
	v_mfma_f32_16x16x32_bf16 v[128:131], v[100:103], v[4:7], v[76:79]
	v_add_u32_e32 v82, s1, v176
	s_nop 1
	v_mfma_f32_16x16x32_bf16 v[116:119], v[112:115], v[12:15], v[116:119]
	v_mfma_f32_16x16x32_bf16 v[186:189], v[112:115], v[16:19], v[108:111]
	v_mfma_f32_16x16x32_bf16 v[198:201], v[96:99], v[16:19], v[84:87]
	ds_read_b64_tr_b16 v[124:125], v82 offset:26624
	ds_read_b64_tr_b16 v[112:113], v82 offset:26656
	ds_read_b64_tr_b16 v[108:109], v82 offset:26688
	ds_read_b64_tr_b16 v[96:97], v82 offset:26720
	ds_read_b64_tr_b16 v[126:127], v82 offset:29184
	ds_read_b64_tr_b16 v[114:115], v82 offset:29216
	ds_read_b64_tr_b16 v[110:111], v82 offset:29248
	ds_read_b64_tr_b16 v[98:99], v82 offset:29280
	v_mfma_f32_16x16x32_bf16 v[136:139], v[100:103], v[8:11], v[92:95]
	v_mfma_f32_16x16x32_bf16 v[132:135], v[120:123], v[4:7], v[88:91]
	s_nop 1
	ds_read_b64_tr_b16 v[92:93], v82 offset:31744
	ds_read_b64_tr_b16 v[88:89], v82 offset:31776
	ds_read_b64_tr_b16 v[84:85], v82 offset:31808
	ds_read_b64_tr_b16 v[80:81], v82 offset:31840
	ds_read_b64_tr_b16 v[94:95], v82 offset:34304
	ds_read_b64_tr_b16 v[90:91], v82 offset:34336
	ds_read_b64_tr_b16 v[86:87], v82 offset:34368
	ds_read_b64_tr_b16 v[82:83], v82 offset:34400
	v_mfma_f32_16x16x32_bf16 v[140:143], v[120:123], v[8:11], v[104:107]
	v_mfma_f32_16x16x32_bf16 v[116:119], v[182:185], v[8:11], v[116:119]
	v_mfma_f32_16x16x32_bf16 v[100:103], v[182:185], v[4:7], v[186:189]
	s_waitcnt lgkmcnt(14)
	v_mfma_f32_16x16x32_bf16 v[120:123], v[190:193], v[8:11], v[194:197]
	v_mfma_f32_16x16x32_bf16 v[104:107], v[190:193], v[4:7], v[198:201]
	v_max3_f32 v181, v136, v137, v138
	v_max3_f32 v183, v128, v129, v130
	v_max3_f32 v184, v131, v132, v133
	v_max3_f32 v181, v181, v139, v140
	v_max3_f32 v183, v183, v134, v135
	v_max3_f32 v181, v181, v141, v142
	v_max3_f32 v182, v143, v116, v117
	v_max3_f32 v184, v184, v100, v101
	v_max3_f32 v182, v182, v118, v119
	v_max3_f32 v184, v184, v102, v103
	v_max3_f32 v181, v181, v120, v121
	v_max3_f32 v182, v182, v122, v123
	v_max3_f32 v183, v183, v104, v105
	v_max3_f32 v184, v184, v106, v107
	v_max_f32_e32 v181, v181, v182
	v_max_f32_e32 v183, v183, v184
	v_max_f32_e32 v184, v181, v183
	v_cmp_lt_f32_e32 vcc, s36, v184
	s_cbranch_vccz .LmB_1378
	v_mov_b32_e32 v182, v181
	v_mov_b32_e32 v184, v183
	s_nop 1
	v_permlane16_swap_b32_e32 v181, v182
	v_permlane16_swap_b32_e32 v183, v184
	v_max_f32_e32 v181, v181, v182
	v_max_f32_e32 v183, v183, v184
	v_mov_b32_e32 v182, v181
	v_mov_b32_e32 v184, v183
	s_nop 1
	v_permlane32_swap_b32_e32 v181, v182
	v_permlane32_swap_b32_e32 v183, v184
	v_max_f32_e32 v182, v181, v182
	v_max_f32_e32 v181, v183, v184
	v_max_f32_e32 v182, v182, v182
	v_max_f32_e32 v183, 0, v182
	v_exp_f32_e64 v182, -v183
	v_max_f32_e32 v181, v181, v181
	v_sub_f32_e32 v136, v136, v183
	v_sub_f32_e32 v137, v137, v183
	v_pk_mul_f32 v[70:71], v[70:71], v[182:183] op_sel_hi:[1,0]
	v_pk_mul_f32 v[68:69], v[68:69], v[182:183] op_sel_hi:[1,0]
	v_pk_mul_f32 v[62:63], v[62:63], v[182:183] op_sel_hi:[1,0]
	v_pk_mul_f32 v[60:61], v[60:61], v[182:183] op_sel_hi:[1,0]
	v_pk_mul_f32 v[54:55], v[54:55], v[182:183] op_sel_hi:[1,0]
	v_pk_mul_f32 v[52:53], v[52:53], v[182:183] op_sel_hi:[1,0]
	v_pk_mul_f32 v[46:47], v[46:47], v[182:183] op_sel_hi:[1,0]
	v_pk_mul_f32 v[44:45], v[44:45], v[182:183] op_sel_hi:[1,0]
	v_pk_mul_f32 v[38:39], v[38:39], v[182:183] op_sel_hi:[1,0]
	v_pk_mul_f32 v[36:37], v[36:37], v[182:183] op_sel_hi:[1,0]
	v_max_f32_e32 v182, 0, v181
	v_exp_f32_e64 v184, -v182
	v_sub_f32_e32 v138, v138, v183
	v_sub_f32_e32 v139, v139, v183
	v_sub_f32_e32 v140, v140, v183
	v_sub_f32_e32 v141, v141, v183
	v_sub_f32_e32 v142, v142, v183
	v_sub_f32_e32 v143, v143, v183
	v_sub_f32_e32 v116, v116, v183
	v_sub_f32_e32 v117, v117, v183
	v_sub_f32_e32 v118, v118, v183
	v_sub_f32_e32 v119, v119, v183
	v_sub_f32_e32 v120, v120, v183
	v_sub_f32_e32 v121, v121, v183
	v_sub_f32_e32 v122, v122, v183
	v_sub_f32_e32 v123, v123, v183
	v_pk_add_f32 v[158:159], v[158:159], v[182:183]
	v_xor_b32_e32 v218, 0x80000000, v159
	v_xor_b32_e32 v222, 0x80000000, v158
	v_mov_b32_e32 v219, v218
	v_mov_b32_e32 v220, v218
	v_mov_b32_e32 v221, v218
	v_mov_b32_e32 v223, v222
	v_mov_b32_e32 v224, v222
	v_mov_b32_e32 v225, v222
	v_sub_f32_e32 v128, v128, v182
	v_sub_f32_e32 v129, v129, v182
	v_sub_f32_e32 v130, v130, v182
	v_sub_f32_e32 v131, v131, v182
	v_sub_f32_e32 v132, v132, v182
	v_sub_f32_e32 v133, v133, v182
	v_sub_f32_e32 v134, v134, v182
	v_sub_f32_e32 v135, v135, v182
	v_sub_f32_e32 v100, v100, v182
	v_sub_f32_e32 v101, v101, v182
	v_sub_f32_e32 v102, v102, v182
	v_sub_f32_e32 v103, v103, v182
	v_sub_f32_e32 v104, v104, v182
	v_sub_f32_e32 v105, v105, v182
	v_sub_f32_e32 v106, v106, v182
	v_sub_f32_e32 v107, v107, v182
	v_pk_mul_f32 v[66:67], v[66:67], v[184:185] op_sel_hi:[1,0]
	v_pk_mul_f32 v[64:65], v[64:65], v[184:185] op_sel_hi:[1,0]
	v_pk_mul_f32 v[58:59], v[58:59], v[184:185] op_sel_hi:[1,0]
	v_pk_mul_f32 v[56:57], v[56:57], v[184:185] op_sel_hi:[1,0]
	v_pk_mul_f32 v[50:51], v[50:51], v[184:185] op_sel_hi:[1,0]
	v_pk_mul_f32 v[48:49], v[48:49], v[184:185] op_sel_hi:[1,0]
	v_pk_mul_f32 v[42:43], v[42:43], v[184:185] op_sel_hi:[1,0]
	v_pk_mul_f32 v[40:41], v[40:41], v[184:185] op_sel_hi:[1,0]
	v_pk_mul_f32 v[34:35], v[34:35], v[184:185] op_sel_hi:[1,0]
	v_pk_mul_f32 v[32:33], v[32:33], v[184:185] op_sel_hi:[1,0]
.LmB_1378:
	s_xor_b32 s99, s0, 1
	s_mul_i32 s46, s99, 0x3400
	v_lshlrev_b32_e32 v240, 1, v170
	v_add3_u32 v240, s46, v240, v180
	s_mulk_i32 s99, 0x2800
	v_add_u32_e32 v241, s99, v174
	s_waitcnt vmcnt(0)
	ds_write_b128 v240, v[232:235]
	ds_write_b128 v241, v[236:239] offset:26624
	s_waitcnt lgkmcnt(0)
	s_barrier
	s_cmp_lt_u32 s27, 34
	s_cbranch_scc0 .LmB_nold
	s_cmp_lt_u32 s27, 30
	s_cselect_b32 s98, s42, s26
	s_lshl_b32 s99, s27, 6
	s_add_i32 s98, s98, s99
	s_lshl_b32 s100, s98, 11
	s_mov_b32 s101, 0
	v_mul_u32_u24_e32 v202, s98, v206
	v_lshl_add_u64 v[232:233], v[204:205], 0, v[202:203]
	global_load_dwordx4 v[232:235], v[232:233], off
	v_lshl_add_u64 v[236:237], v[216:217], 0, s[100:101]
	global_load_dwordx4 v[236:239], v[236:237], off offset:128
.LmB_nold:
	v_exp_f32_e32 v136, v136
	v_exp_f32_e32 v137, v137
	v_exp_f32_e32 v138, v138
	v_exp_f32_e32 v139, v139
	v_exp_f32_e32 v140, v140
	v_exp_f32_e32 v141, v141
	v_exp_f32_e32 v142, v142
	v_exp_f32_e32 v143, v143
	v_exp_f32_e32 v128, v128
	v_exp_f32_e32 v129, v129
	v_exp_f32_e32 v130, v130
	v_exp_f32_e32 v131, v131
	v_exp_f32_e32 v132, v132
	v_exp_f32_e32 v133, v133
	v_exp_f32_e32 v134, v134
	v_exp_f32_e32 v135, v135
	v_cvt_pk_bf16_f32 v136, v136, v137
	v_cvt_pk_bf16_f32 v137, v138, v139
	v_cvt_pk_bf16_f32 v138, v140, v141
	v_cvt_pk_bf16_f32 v139, v142, v143
	v_cvt_pk_bf16_f32 v128, v128, v129
	v_cvt_pk_bf16_f32 v129, v130, v131
	v_cvt_pk_bf16_f32 v130, v132, v133
	v_cvt_pk_bf16_f32 v131, v134, v135
	s_waitcnt lgkmcnt(0)
	v_mfma_f32_16x16x32_bf16 v[60:63], v[112:115], v[136:139], v[60:63]
	v_exp_f32_e32 v116, v116
	s_xor_b32 s43, s0, 1
	s_mul_i32 s46, s43, 0x3400
	v_mfma_f32_16x16x32_bf16 v[56:59], v[112:115], v[128:131], v[56:59]
	v_exp_f32_e32 v112, v117
	v_exp_f32_e32 v113, v118
	v_exp_f32_e32 v114, v119
	v_exp_f32_e32 v115, v120
	v_exp_f32_e32 v117, v121
	v_mfma_f32_16x16x32_bf16 v[52:55], v[108:111], v[136:139], v[52:55]
	v_exp_f32_e32 v118, v122
	v_mfma_f32_16x16x32_bf16 v[48:51], v[108:111], v[128:131], v[48:51]
	v_cvt_pk_bf16_f32 v108, v116, v112
	v_cvt_pk_bf16_f32 v109, v113, v114
	v_cvt_pk_bf16_f32 v110, v115, v117
	v_exp_f32_e32 v111, v123
	v_mfma_f32_16x16x32_bf16 v[44:47], v[96:99], v[136:139], v[44:47]
	v_cvt_pk_bf16_f32 v111, v118, v111
	v_mfma_f32_16x16x32_bf16 v[40:43], v[96:99], v[128:131], v[40:43]
	v_exp_f32_e32 v96, v100
	v_exp_f32_e32 v97, v101
	v_exp_f32_e32 v98, v102
	v_exp_f32_e32 v99, v103
	v_exp_f32_e32 v100, v104
	v_exp_f32_e32 v101, v105
	v_exp_f32_e32 v102, v106
	v_exp_f32_e32 v103, v107
	v_mfma_f32_16x16x32_bf16 v[68:71], v[124:127], v[136:139], v[68:71]
	v_cvt_pk_bf16_f32 v96, v96, v97
	v_cvt_pk_bf16_f32 v97, v98, v99
	v_cvt_pk_bf16_f32 v98, v100, v101
	v_mfma_f32_16x16x32_bf16 v[64:67], v[124:127], v[128:131], v[64:67]
	v_cvt_pk_bf16_f32 v99, v102, v103
	v_mfma_f32_16x16x32_bf16 v[36:39], v[228:231], v[136:139], v[36:39]
	v_mfma_f32_16x16x32_bf16 v[32:35], v[228:231], v[128:131], v[32:35]
	v_mfma_f32_16x16x32_bf16 v[68:71], v[92:95], v[108:111], v[68:71]
	v_mfma_f32_16x16x32_bf16 v[64:67], v[92:95], v[96:99], v[64:67]
	v_mfma_f32_16x16x32_bf16 v[60:63], v[88:91], v[108:111], v[60:63]
	v_mfma_f32_16x16x32_bf16 v[56:59], v[88:91], v[96:99], v[56:59]
	v_mfma_f32_16x16x32_bf16 v[52:55], v[84:87], v[108:111], v[52:55]
	v_mfma_f32_16x16x32_bf16 v[48:51], v[84:87], v[96:99], v[48:51]
	v_mfma_f32_16x16x32_bf16 v[44:47], v[80:83], v[108:111], v[44:47]
	v_mfma_f32_16x16x32_bf16 v[40:43], v[80:83], v[96:99], v[40:43]
	v_mfma_f32_16x16x32_bf16 v[36:39], v[228:231], v[108:111], v[36:39]
	v_mfma_f32_16x16x32_bf16 v[32:35], v[228:231], v[96:99], v[32:35]
	s_branch .LmB_1373
.LmA_exit:
	s_barrier
.LBB0_1380:
	ds_read_b128 v[28:31], v175 offset:13312
	ds_read_b128 v[80:83], v175 offset:13376
	v_xor_b32_e32 v72, 0x80000000, v159
	v_xor_b32_e32 v76, 0x80000000, v158
	v_mov_b32_e32 v73, v72
	v_mov_b32_e32 v74, v72
	v_mov_b32_e32 v75, v72
	v_mov_b32_e32 v77, v76
	v_mov_b32_e32 v78, v76
	v_mov_b32_e32 v79, v76
	s_waitcnt lgkmcnt(1)
	v_mfma_f32_16x16x32_bf16 v[84:87], v[28:31], v[20:23], v[72:75]
	ds_read_b128 v[88:91], v175 offset:16640
	ds_read_b128 v[92:95], v175 offset:13440
	ds_read_b128 v[100:103], v175 offset:19968
	ds_read_b128 v[104:107], v175 offset:20032
	ds_read_b128 v[112:115], v175 offset:23296
	ds_read_b128 v[116:119], v175 offset:20096
	v_mfma_f32_16x16x32_bf16 v[28:31], v[28:31], v[24:27], v[76:79]
	s_waitcnt lgkmcnt(5)
	v_mfma_f32_16x16x32_bf16 v[96:99], v[88:91], v[20:23], v[72:75]
	v_mfma_f32_16x16x32_bf16 v[88:91], v[88:91], v[24:27], v[76:79]
	s_waitcnt lgkmcnt(3)
	v_mfma_f32_16x16x32_bf16 v[108:111], v[100:103], v[20:23], v[72:75]
	v_mfma_f32_16x16x32_bf16 v[100:103], v[100:103], v[24:27], v[76:79]
	s_waitcnt lgkmcnt(1)
	v_mfma_f32_16x16x32_bf16 v[20:23], v[112:115], v[20:23], v[72:75]
	v_mfma_f32_16x16x32_bf16 v[24:27], v[112:115], v[24:27], v[76:79]
	v_mfma_f32_16x16x32_bf16 v[72:75], v[80:83], v[12:15], v[84:87]
	v_mfma_f32_16x16x32_bf16 v[28:31], v[80:83], v[16:19], v[28:31]
	s_nop 0
	ds_read_b128 v[76:79], v175 offset:16704
	ds_read_b128 v[80:83], v175 offset:16768
	s_waitcnt lgkmcnt(1)
	v_mfma_f32_16x16x32_bf16 v[84:87], v[76:79], v[12:15], v[96:99]
	v_mfma_f32_16x16x32_bf16 v[76:79], v[76:79], v[16:19], v[88:91]
	s_nop 2
	ds_read_b128 v[88:91], v175 offset:23360
	ds_read_b128 v[120:123], v175 offset:23424
	v_mfma_f32_16x16x32_bf16 v[108:111], v[104:107], v[12:15], v[108:111]
	v_mfma_f32_16x16x32_bf16 v[112:115], v[104:107], v[16:19], v[100:103]
	s_waitcnt lgkmcnt(1)
	v_mfma_f32_16x16x32_bf16 v[124:127], v[88:91], v[12:15], v[20:23]
	v_mfma_f32_16x16x32_bf16 v[128:131], v[88:91], v[16:19], v[24:27]
	v_mfma_f32_16x16x32_bf16 v[104:107], v[92:95], v[8:11], v[72:75]
	v_mfma_f32_16x16x32_bf16 v[96:99], v[92:95], v[4:7], v[28:31]
	v_mfma_f32_16x16x32_bf16 v[100:103], v[80:83], v[8:11], v[84:87]
	v_mfma_f32_16x16x32_bf16 v[92:95], v[80:83], v[4:7], v[76:79]
	ds_read_b64_tr_b16 v[88:89], v176 offset:36864
	ds_read_b64_tr_b16 v[80:81], v176 offset:36896
	s_nop 0
	ds_read_b64_tr_b16 v[76:77], v176 offset:36928
	ds_read_b64_tr_b16 v[28:29], v176 offset:36960
	ds_read_b64_tr_b16 v[90:91], v176 offset:39424
	ds_read_b64_tr_b16 v[82:83], v176 offset:39456
	ds_read_b64_tr_b16 v[78:79], v176 offset:39488
	ds_read_b64_tr_b16 v[30:31], v176 offset:39520
	ds_read_b64_tr_b16 v[24:25], v176 offset:41984
	ds_read_b64_tr_b16 v[20:21], v176 offset:42016
	ds_read_b64_tr_b16 v[16:17], v176 offset:42048
	ds_read_b64_tr_b16 v[12:13], v176 offset:42080
	ds_read_b64_tr_b16 v[26:27], v176 offset:44544
	ds_read_b64_tr_b16 v[22:23], v176 offset:44576
	ds_read_b64_tr_b16 v[18:19], v176 offset:44608
	ds_read_b64_tr_b16 v[14:15], v176 offset:44640
	v_mfma_f32_16x16x32_bf16 v[84:87], v[116:119], v[8:11], v[108:111]
	v_mfma_f32_16x16x32_bf16 v[72:75], v[116:119], v[4:7], v[112:115]
	s_waitcnt lgkmcnt(14)
	v_mfma_f32_16x16x32_bf16 v[8:11], v[120:123], v[8:11], v[124:127]
	v_mfma_f32_16x16x32_bf16 v[4:7], v[120:123], v[4:7], v[128:131]
	v_max_f32_e32 v108, v105, v105
	v_max_f32_e32 v109, v104, v104
	v_max_f32_e32 v108, v109, v108
	v_max_f32_e32 v109, v107, v107
	v_max_f32_e32 v110, v106, v106
	v_max_f32_e32 v109, v110, v109
	v_max_f32_e32 v110, v103, v103
	v_max_f32_e32 v111, v102, v102
	v_max_f32_e32 v110, v111, v110
	v_max3_f32 v110, v100, v101, v110
	v_max3_f32 v108, v108, v109, v110
	v_max_f32_e32 v109, v87, v87
	v_max_f32_e32 v110, v86, v86
	v_max_f32_e32 v109, v110, v109
	v_max_f32_e32 v110, v11, v11
	v_max_f32_e32 v111, v10, v10
	v_max_f32_e32 v110, v111, v110
	v_max3_f32 v109, v84, v85, v109
	v_max3_f32 v110, v8, v9, v110
	v_max3_f32 v108, v108, v109, v110
	v_max_f32_e32 v110, v97, v97
	v_max_f32_e32 v111, v96, v96
	v_max_f32_e32 v110, v111, v110
	v_max_f32_e32 v111, v99, v99
	v_max_f32_e32 v112, v98, v98
	v_max_f32_e32 v111, v112, v111
	v_max_f32_e32 v112, v95, v95
	v_max_f32_e32 v113, v94, v94
	v_max_f32_e32 v112, v113, v112
	v_max3_f32 v112, v92, v93, v112
	v_max3_f32 v110, v110, v111, v112
	v_max_f32_e32 v111, v75, v75
	v_max_f32_e32 v112, v74, v74
	v_max_f32_e32 v111, v112, v111
	v_max_f32_e32 v112, v7, v7
	v_max_f32_e32 v113, v6, v6
	v_max_f32_e32 v112, v113, v112
	v_max3_f32 v111, v72, v73, v111
	v_max3_f32 v112, v4, v5, v112
	ds_bpermute_b32 v109, v173, v108
	v_max3_f32 v110, v110, v111, v112
	ds_bpermute_b32 v111, v173, v110
	s_waitcnt lgkmcnt(1)
	v_max_f32_e32 v109, v109, v109
	v_max_f32_e32 v108, v108, v109
	s_waitcnt lgkmcnt(0)
	v_max_f32_e32 v111, v111, v111
	ds_bpermute_b32 v109, v172, v108
	v_max_f32_e32 v110, v110, v111
	ds_bpermute_b32 v111, v172, v110
	s_waitcnt lgkmcnt(1)
	v_max_f32_e32 v109, v109, v109
	v_max_f32_e32 v109, v108, v109
	s_waitcnt lgkmcnt(0)
	v_max_f32_e32 v108, v111, v111
	v_max_f32_e32 v108, v110, v108
	v_max_f32_e32 v110, v109, v108
	v_cmp_lt_f32_e32 vcc, s36, v110
	s_cbranch_vccz .LBB0_1350
	v_max_f32_e32 v109, v109, v109
	v_max_f32_e32 v109, 0, v109
	v_max_f32_e32 v108, v108, v108
	v_sub_f32_e32 v104, v104, v109
	v_sub_f32_e32 v105, v105, v109
	v_sub_f32_e32 v106, v106, v109
	v_sub_f32_e32 v107, v107, v109
	v_sub_f32_e32 v100, v100, v109
	v_sub_f32_e32 v101, v101, v109
	v_sub_f32_e32 v102, v102, v109
	v_sub_f32_e32 v103, v103, v109
	v_sub_f32_e32 v84, v84, v109
	v_sub_f32_e32 v85, v85, v109
	v_sub_f32_e32 v86, v86, v109
	v_sub_f32_e32 v87, v87, v109
	v_sub_f32_e32 v8, v8, v109
	v_exp_f32_e64 v110, -v109
	v_sub_f32_e32 v9, v9, v109
	v_sub_f32_e32 v10, v10, v109
	v_sub_f32_e32 v11, v11, v109
	v_max_f32_e32 v109, 0, v108
	v_exp_f32_e64 v108, -v109
	v_pk_mul_f32 v[70:71], v[70:71], v[110:111] op_sel_hi:[1,0]
	v_pk_mul_f32 v[68:69], v[68:69], v[110:111] op_sel_hi:[1,0]
	v_pk_mul_f32 v[62:63], v[62:63], v[110:111] op_sel_hi:[1,0]
	v_pk_mul_f32 v[60:61], v[60:61], v[110:111] op_sel_hi:[1,0]
	v_pk_mul_f32 v[54:55], v[54:55], v[110:111] op_sel_hi:[1,0]
	v_pk_mul_f32 v[52:53], v[52:53], v[110:111] op_sel_hi:[1,0]
	v_pk_mul_f32 v[46:47], v[46:47], v[110:111] op_sel_hi:[1,0]
	v_pk_mul_f32 v[44:45], v[44:45], v[110:111] op_sel_hi:[1,0]
	v_pk_mul_f32 v[38:39], v[38:39], v[110:111] op_sel_hi:[1,0]
	v_pk_mul_f32 v[36:37], v[36:37], v[110:111] op_sel_hi:[1,0]
	v_sub_f32_e32 v96, v96, v109
	v_sub_f32_e32 v97, v97, v109
	v_sub_f32_e32 v98, v98, v109
	v_sub_f32_e32 v99, v99, v109
	v_sub_f32_e32 v92, v92, v109
	v_sub_f32_e32 v93, v93, v109
	v_sub_f32_e32 v94, v94, v109
	v_sub_f32_e32 v95, v95, v109
	v_sub_f32_e32 v72, v72, v109
	v_sub_f32_e32 v73, v73, v109
	v_sub_f32_e32 v74, v74, v109
	v_sub_f32_e32 v75, v75, v109
	v_sub_f32_e32 v4, v4, v109
	v_sub_f32_e32 v5, v5, v109
	v_sub_f32_e32 v6, v6, v109
	v_sub_f32_e32 v7, v7, v109
	v_pk_mul_f32 v[66:67], v[66:67], v[108:109] op_sel_hi:[1,0]
	v_pk_mul_f32 v[64:65], v[64:65], v[108:109] op_sel_hi:[1,0]
	v_pk_mul_f32 v[58:59], v[58:59], v[108:109] op_sel_hi:[1,0]
	v_pk_mul_f32 v[56:57], v[56:57], v[108:109] op_sel_hi:[1,0]
	v_pk_mul_f32 v[50:51], v[50:51], v[108:109] op_sel_hi:[1,0]
	v_pk_mul_f32 v[48:49], v[48:49], v[108:109] op_sel_hi:[1,0]
	v_pk_mul_f32 v[42:43], v[42:43], v[108:109] op_sel_hi:[1,0]
	v_pk_mul_f32 v[40:41], v[40:41], v[108:109] op_sel_hi:[1,0]
	v_pk_mul_f32 v[34:35], v[34:35], v[108:109] op_sel_hi:[1,0]
	v_pk_mul_f32 v[32:33], v[32:33], v[108:109] op_sel_hi:[1,0]
	s_branch .LBB0_1350
